# Differential attention: key-tile list byte read once per tile (was three dependent LDS round trips before the three LDS-DMA issues)
# speedup vs baseline: 1.0151x; 1.0016x over previous
;     __device__ __forceinline__ int k_row(int t, int j) const { return (kr_lo + t) * 64 + j; }
; template <int KSTEPS, class Pol>
; __device__ __forceinline__ void attn_pass(LAS unsigned char* lds, const Pol& P, const bf16_t* qb, int ldq, const bf16_t* kb, int ldk, const bf16_t* vb, int ldv,
;                                           float qs, f32x16 (&O)[4], float& m, float& l) {
;     ...
;     auto dma = [&](int t, int st) __attribute__((always_inline)) {
;         const unsigned sbase = (unsigned)(size_t)lds + (unsigned)(st * A_STAGE);
; #pragma unroll
;         for (int j = 0; j < NKI; ++j) {
;             const int inst = wave * NKI + j;
;             if (KSTEPS == 8) { const int row = inst * 4 + (lane >> 4), slot = lane & 15, c = slot ^ (row & 15);
;                 dma16(kb + (size_t)P.k_row(t, row) * ldk + c * 8, sbase + inst * 1024);
;             } else { const int row = inst * 8 + (lane >> 3), slot = lane & 7, c = slot ^ ((row >> 1) & 7);
;                 dma16(kb + (size_t)P.k_row(t, row) * ldk + c * 8, sbase + inst * 1024); }
;         }
; #pragma unroll
;         for (int j = 0; j < 2; ++j) {
;             const int inst = wave * 2 + j, row = inst * 4 + (lane >> 4), slot = lane & 15, c = slot ^ (((row & 3) << 2) | ((row >> 2) & 3));
;             dma16(vb + (size_t)P.k_row(t, row) * ldv + c * 8, sbase + 16384 + inst * 1024);
;         }
.LBB0_499:
	s_andn2_b64 vcc, exec, s[36:37]
	s_cbranch_vccnz .LBB0_501
	s_lshl_b32 s51, s49, 15
	s_add_i32 s36, s51, 0xffff8000
	s_cmp_gt_i32 s49, 0
	s_cselect_b32 s40, s36, 0x10000
	s_add_i32 s36, s48, 0
	s_add_i32 s36, s36, 0x18802
	v_mov_b32_e32 v0, s36
	ds_read_u8 v201, v0
	s_waitcnt lgkmcnt(0)
	v_lshl_add_u32 v2, v201, 6, v129
	v_mad_i64_i32 v[2:3], s[36:37], v2, s67, v[132:133]
	s_add_i32 s36, s40, s42
	s_mov_b32 m0, s36
	s_nop 0
	global_load_lds_dwordx4 v[2:3], off
	s_add_i32 s36, s40, 0
	s_add_i32 s40, s36, 0x4000
	v_lshl_add_u32 v2, v201, 6, v130
	v_mad_i64_i32 v[2:3], s[36:37], v2, s67, v[134:135]
	s_add_i32 s36, s40, s43
	s_mov_b32 m0, s36
	s_nop 0
	global_load_lds_dwordx4 v[2:3], off
	s_add_i32 s40, s40, s45
	v_lshl_add_u32 v0, v201, 6, v149
	v_mad_i64_i32 v[2:3], s[36:37], v0, s67, v[136:137]
	s_mov_b32 m0, s40
	s_nop 0
	global_load_lds_dwordx4 v[2:3], off
